# gate buffer layout: lane's two 16-col fragments adjacent; F0 stores dwordx4, F1 loads gates with 8 dwordx4 instead of 16 dwordx2
# speedup vs baseline: 1.0076x; 1.0032x over previous
.LBB0_161:
	s_waitcnt vmcnt(0)
	v_lshlrev_b32_e32 v178, 16, v174
	v_and_b32_e32 v179, 0xffff0000, v174
	v_pk_fma_f32 v[142:143], v[60:61], v[178:179], v[142:143]
	v_lshlrev_b32_e32 v60, 16, v175
	v_and_b32_e32 v61, 0xffff0000, v175
	v_pk_fma_f32 v[144:145], v[62:63], v[60:61], v[144:145]
	v_lshlrev_b32_e32 v60, 16, v176
	v_and_b32_e32 v61, 0xffff0000, v176
	v_pk_fma_f32 v[138:139], v[56:57], v[60:61], v[138:139]
	v_lshlrev_b32_e32 v56, 16, v177
	v_and_b32_e32 v57, 0xffff0000, v177
	v_pk_fma_f32 v[140:141], v[58:59], v[56:57], v[140:141]
	v_lshlrev_b32_e32 v56, 16, v170
	v_and_b32_e32 v57, 0xffff0000, v170
	v_pk_fma_f32 v[134:135], v[52:53], v[56:57], v[134:135]
	v_lshlrev_b32_e32 v52, 16, v171
	v_and_b32_e32 v53, 0xffff0000, v171
	v_pk_fma_f32 v[136:137], v[54:55], v[52:53], v[136:137]
	v_lshlrev_b32_e32 v52, 16, v172
	v_and_b32_e32 v53, 0xffff0000, v172
	v_pk_fma_f32 v[130:131], v[48:49], v[52:53], v[130:131]
	v_lshlrev_b32_e32 v48, 16, v173
	v_and_b32_e32 v49, 0xffff0000, v173
	v_pk_fma_f32 v[132:133], v[50:51], v[48:49], v[132:133]
	v_lshlrev_b32_e32 v48, 16, v166
	v_and_b32_e32 v49, 0xffff0000, v166
	v_pk_fma_f32 v[122:123], v[44:45], v[48:49], v[122:123]
	v_lshlrev_b32_e32 v44, 16, v167
	v_and_b32_e32 v45, 0xffff0000, v167
	v_pk_fma_f32 v[124:125], v[46:47], v[44:45], v[124:125]
	v_lshlrev_b32_e32 v44, 16, v168
	v_and_b32_e32 v45, 0xffff0000, v168
	v_pk_fma_f32 v[98:99], v[40:41], v[44:45], v[98:99]
	v_lshlrev_b32_e32 v40, 16, v169
	v_and_b32_e32 v41, 0xffff0000, v169
	v_pk_fma_f32 v[102:103], v[42:43], v[40:41], v[102:103]
	v_lshlrev_b32_e32 v40, 16, v162
	v_and_b32_e32 v41, 0xffff0000, v162
	v_pk_fma_f32 v[78:79], v[36:37], v[40:41], v[78:79]
	v_lshlrev_b32_e32 v36, 16, v163
	v_and_b32_e32 v37, 0xffff0000, v163
	v_pk_fma_f32 v[80:81], v[38:39], v[36:37], v[80:81]
	v_lshlrev_b32_e32 v36, 16, v164
	v_and_b32_e32 v37, 0xffff0000, v164
	v_pk_fma_f32 v[72:73], v[32:33], v[36:37], v[72:73]
	v_lshlrev_b32_e32 v32, 16, v165
	v_and_b32_e32 v33, 0xffff0000, v165
	v_pk_fma_f32 v[74:75], v[34:35], v[32:33], v[74:75]
	v_lshlrev_b32_e32 v32, 16, v158
	v_and_b32_e32 v33, 0xffff0000, v158
	v_pk_fma_f32 v[118:119], v[28:29], v[32:33], v[118:119]
	v_lshlrev_b32_e32 v28, 16, v159
	v_and_b32_e32 v29, 0xffff0000, v159
	v_pk_fma_f32 v[120:121], v[30:31], v[28:29], v[120:121]
	v_lshlrev_b32_e32 v28, 16, v160
	v_and_b32_e32 v29, 0xffff0000, v160
	v_pk_fma_f32 v[110:111], v[24:25], v[28:29], v[110:111]
	v_lshlrev_b32_e32 v24, 16, v161
	v_and_b32_e32 v25, 0xffff0000, v161
	v_pk_fma_f32 v[116:117], v[26:27], v[24:25], v[116:117]
	v_lshlrev_b32_e32 v24, 16, v154
	v_and_b32_e32 v25, 0xffff0000, v154
	v_pk_fma_f32 v[106:107], v[20:21], v[24:25], v[106:107]
	v_lshlrev_b32_e32 v20, 16, v155
	v_and_b32_e32 v21, 0xffff0000, v155
	v_pk_fma_f32 v[112:113], v[22:23], v[20:21], v[112:113]
	v_lshlrev_b32_e32 v20, 16, v156
	v_and_b32_e32 v21, 0xffff0000, v156
	v_pk_fma_f32 v[104:105], v[16:17], v[20:21], v[104:105]
	v_lshlrev_b32_e32 v16, 16, v157
	v_and_b32_e32 v17, 0xffff0000, v157
	v_pk_fma_f32 v[108:109], v[18:19], v[16:17], v[108:109]
	v_lshlrev_b32_e32 v16, 16, v150
	v_and_b32_e32 v17, 0xffff0000, v150
	v_pk_fma_f32 v[96:97], v[12:13], v[16:17], v[96:97]
	v_lshlrev_b32_e32 v12, 16, v151
	v_and_b32_e32 v13, 0xffff0000, v151
	v_pk_fma_f32 v[100:101], v[14:15], v[12:13], v[100:101]
	v_lshlrev_b32_e32 v12, 16, v152
	v_and_b32_e32 v13, 0xffff0000, v152
	v_pk_fma_f32 v[88:89], v[8:9], v[12:13], v[88:89]
	v_lshlrev_b32_e32 v8, 16, v153
	v_and_b32_e32 v9, 0xffff0000, v153
	v_pk_fma_f32 v[92:93], v[10:11], v[8:9], v[92:93]
	v_lshlrev_b32_e32 v8, 16, v146
	v_and_b32_e32 v9, 0xffff0000, v146
	v_pk_fma_f32 v[84:85], v[4:5], v[8:9], v[84:85]
	v_lshlrev_b32_e32 v4, 16, v147
	v_and_b32_e32 v5, 0xffff0000, v147
	v_pk_fma_f32 v[90:91], v[6:7], v[4:5], v[90:91]
	v_lshlrev_b32_e32 v4, 16, v148
	v_and_b32_e32 v5, 0xffff0000, v148
	v_pk_fma_f32 v[82:83], v[0:1], v[4:5], v[82:83]
	v_lshlrev_b32_e32 v0, 16, v149
	v_and_b32_e32 v1, 0xffff0000, v149
	s_add_i32 s11, s11, 1
	s_cmp_eq_u32 s11, 3
	v_pk_fma_f32 v[86:87], v[2:3], v[0:1], v[86:87]
	s_cbranch_scc1 .LBB0_159
.LBB0_162:
	s_lshl_b32 s0, s11, 11
	s_add_u32 s2, s94, s0
	s_addc_u32 s3, s95, 0
	v_lshrrev_b32_e32 v188, 1, v204
	v_and_b32_e32 v188, 24, v188
	v_lshl_add_u64 v[2:3], v[66:67], 0, v[188:189]
	v_lshl_add_u64 v[0:1], s[2:3], 0, v[94:95]
	v_lshl_add_u64 v[0:1], v[0:1], 0, v[2:3]
	global_load_dwordx4 v[174:177], v[0:1], off
	global_load_dwordx4 v[170:173], v[0:1], off offset:64
	v_lshl_add_u64 v[0:1], s[2:3], 0, v[114:115]
	v_lshl_add_u64 v[0:1], v[0:1], 0, v[2:3]
	global_load_dwordx4 v[166:169], v[0:1], off
	global_load_dwordx4 v[162:165], v[0:1], off offset:64
	v_lshl_add_u64 v[0:1], s[2:3], 0, v[126:127]
	v_lshl_add_u64 v[0:1], v[0:1], 0, v[2:3]
	global_load_dwordx4 v[158:161], v[0:1], off
	global_load_dwordx4 v[154:157], v[0:1], off offset:64
	v_lshl_add_u64 v[0:1], s[2:3], 0, v[128:129]
	v_lshl_add_u64 v[0:1], v[0:1], 0, v[2:3]
	global_load_dwordx4 v[150:153], v[0:1], off
	global_load_dwordx4 v[146:149], v[0:1], off offset:64
	s_cmp_eq_u32 s11, 1
	s_mov_b32 s3, 0x530000
	s_cselect_b32 s0, s88, s82
	s_cselect_b32 s2, s89, s83
	s_cselect_b32 s4, s3, 0x630000
	s_cselect_b32 s12, 16, 8
	s_cselect_b32 s13, 10, 9
	s_cmp_eq_u32 s11, 0
	s_cselect_b32 s3, s81, s2
	s_cselect_b32 s2, s80, s0
	s_cselect_b32 s0, 0x4b0000, s4
	s_lshl_b32 s0, s0, 1
	v_mov_b32_e32 v4, v204
	s_add_u32 s4, s97, s0
	v_readfirstlane_b32 s14, v4
	s_addc_u32 s5, s79, 0
	s_ashr_i32 s15, s14, 6
	v_bfe_u32 v0, v4, 3, 3
	s_and_b32 s16, s15, 1
	v_lshl_or_b32 v5, s15, 3, v0
	v_and_b32_e32 v0, 7, v4
	s_lshl_b32 s0, s16, 2
	v_bfe_u32 v6, v4, 4, 2
	v_bitop3_b32 v7, s0, v0, v6 bitop3:0x36
	v_add_u32_e32 v0, s9, v5
	v_ashrrev_i32_e32 v1, 31, v0
	v_lshlrev_b64 v[2:3], s13, v[0:1]
	v_lshl_add_u64 v[2:3], v[2:3], 1, s[2:3]
	v_lshlrev_b32_e32 v188, 4, v7
	v_lshl_add_u64 v[178:179], v[2:3], 0, v[188:189]
	v_add_u32_e32 v2, 64, v0
	v_ashrrev_i32_e32 v3, 31, v2
	v_lshlrev_b64 v[2:3], s13, v[2:3]
	v_lshl_add_u64 v[2:3], v[2:3], 1, s[2:3]
	v_lshl_add_u64 v[180:181], v[2:3], 0, v[188:189]
	v_add_u32_e32 v2, 0x80, v0
	v_add_u32_e32 v0, 0xc0, v0
	v_ashrrev_i32_e32 v1, 31, v0
	v_lshlrev_b64 v[0:1], s13, v[0:1]
	v_ashrrev_i32_e32 v3, 31, v2
	v_lshl_add_u64 v[0:1], v[0:1], 1, s[2:3]
	v_lshlrev_b64 v[2:3], s13, v[2:3]
	v_lshl_add_u64 v[184:185], v[0:1], 0, v[188:189]
	v_add_u32_e32 v0, s10, v5
	v_lshl_add_u64 v[2:3], v[2:3], 1, s[2:3]
	v_ashrrev_i32_e32 v1, 31, v0
	v_lshl_add_u64 v[182:183], v[2:3], 0, v[188:189]
	v_lshlrev_b64 v[2:3], s13, v[0:1]
	v_add_u32_e32 v0, 64, v0
	v_ashrrev_i32_e32 v1, 31, v0
	s_lshl_b32 s2, s15, 10
	v_lshlrev_b64 v[0:1], s13, v[0:1]
	s_add_i32 s13, s2, 0
	s_mov_b32 m0, s13
	v_lshl_add_u64 v[2:3], v[2:3], 1, s[4:5]
	global_load_lds_dwordx4 v[178:179], off
	s_add_i32 m0, s13, 0x2000
	v_lshl_add_u64 v[186:187], v[2:3], 0, v[188:189]
	global_load_lds_dwordx4 v[180:181], off
	s_add_i32 m0, s13, 0x4000
	v_lshl_add_u64 v[0:1], v[0:1], 1, s[4:5]
	global_load_lds_dwordx4 v[182:183], off
	s_add_i32 m0, s13, 0x6000
	v_lshl_add_u64 v[190:191], v[0:1], 0, v[188:189]
	global_load_lds_dwordx4 v[184:185], off
	s_add_i32 m0, s13, 0x8000
	v_lshl_add_u64 v[0:1], v[178:179], 0, s[92:93]
	global_load_lds_dwordx4 v[186:187], off
	s_add_i32 m0, s13, 0xa000
	s_lshr_b32 s2, s14, 1
	global_load_lds_dwordx4 v[190:191], off
	s_add_i32 m0, s13, 0xc000
	s_and_b32 s2, s2, 0x1ffffc0
	global_load_lds_dwordx4 v[0:1], off
	v_lshl_add_u64 v[0:1], v[180:181], 0, s[92:93]
	s_add_i32 m0, s13, 0xe000
	s_movk_i32 s0, 0x80
	global_load_lds_dwordx4 v[0:1], off
	v_lshl_add_u64 v[0:1], v[182:183], 0, s[92:93]
	s_add_i32 m0, s13, 0x10000
	s_lshl_b32 s14, s16, 13
	global_load_lds_dwordx4 v[0:1], off
	v_lshl_add_u64 v[0:1], v[184:185], 0, s[92:93]
	s_add_i32 m0, s13, 0x12000
	s_mov_b32 s15, 0
	global_load_lds_dwordx4 v[0:1], off
	v_lshl_add_u64 v[0:1], v[186:187], 0, s[92:93]
	s_add_i32 m0, s13, 0x14000
	s_mov_b32 s16, 0
	global_load_lds_dwordx4 v[0:1], off
	v_lshl_add_u64 v[0:1], v[190:191], 0, s[92:93]
	s_add_i32 m0, s13, 0x16000
	v_mov_b32_e32 v2, v192
	global_load_lds_dwordx4 v[0:1], off
	s_waitcnt vmcnt(6)
	v_bfe_u32 v1, v4, 1, 3
	s_waitcnt lgkmcnt(0)
	s_barrier
	v_and_b32_e32 v0, 15, v4
	v_xor_b32_e32 v1, v6, v1
	v_lshlrev_b32_e32 v188, 4, v1
	v_or_b32_e32 v1, s2, v0
	v_lshlrev_b32_e32 v193, 7, v1
	v_lshlrev_b32_e32 v194, 7, v0
	v_xor_b32_e32 v195, 64, v188
	v_mov_b32_e32 v0, 0
	v_mov_b32_e32 v1, v192
	v_mov_b32_e32 v3, v192
	v_mov_b32_e32 v4, 0
	v_mov_b32_e32 v5, v192
	v_mov_b32_e32 v6, v192
	v_mov_b32_e32 v7, v192
	v_mov_b32_e32 v8, 0
	v_mov_b32_e32 v9, v192
	v_mov_b32_e32 v10, v192
	v_mov_b32_e32 v11, v192
	v_mov_b32_e32 v12, 0
	v_mov_b32_e32 v13, v192
	v_mov_b32_e32 v14, v192
	v_mov_b32_e32 v15, v192
	v_mov_b32_e32 v16, 0
	v_mov_b32_e32 v17, v192
	v_mov_b32_e32 v18, v192
	v_mov_b32_e32 v19, v192
	v_mov_b32_e32 v20, 0
	v_mov_b32_e32 v21, v192
	v_mov_b32_e32 v22, v192
	v_mov_b32_e32 v23, v192
	v_mov_b32_e32 v24, 0
	v_mov_b32_e32 v25, v192
	v_mov_b32_e32 v26, v192
	v_mov_b32_e32 v27, v192
	v_mov_b32_e32 v28, 0
	v_mov_b32_e32 v29, v192
	v_mov_b32_e32 v30, v192
	v_mov_b32_e32 v31, v192
	v_mov_b32_e32 v32, 0
	v_mov_b32_e32 v33, v192
	v_mov_b32_e32 v34, v192
	v_mov_b32_e32 v35, v192
	v_mov_b32_e32 v36, 0
	v_mov_b32_e32 v37, v192
	v_mov_b32_e32 v38, v192
	v_mov_b32_e32 v39, v192
	v_mov_b32_e32 v40, 0
	v_mov_b32_e32 v41, v192
	v_mov_b32_e32 v42, v192
	v_mov_b32_e32 v43, v192
	v_mov_b32_e32 v44, 0
	v_mov_b32_e32 v45, v192
	v_mov_b32_e32 v46, v192
	v_mov_b32_e32 v47, v192
	v_mov_b32_e32 v48, 0
	v_mov_b32_e32 v49, v192
	v_mov_b32_e32 v50, v192
	v_mov_b32_e32 v51, v192
	v_mov_b32_e32 v52, 0
	v_mov_b32_e32 v53, v192
	v_mov_b32_e32 v54, v192
	v_mov_b32_e32 v55, v192
	v_mov_b32_e32 v56, 0
	v_mov_b32_e32 v57, v192
	v_mov_b32_e32 v58, v192
	v_mov_b32_e32 v59, v192
	v_mov_b32_e32 v60, 0
	v_mov_b32_e32 v61, v192
	v_mov_b32_e32 v62, v192
	v_mov_b32_e32 v63, v192
	s_branch .LBB0_164

.LBB0_180:
	v_bfe_u32 v16, v6, 4, 2
	v_and_b32_e32 v7, 15, v6
	v_lshlrev_b32_e32 v17, 4, v16
	v_lshlrev_b32_e32 v6, 2, v6
	s_lshl_b32 s0, s0, 5
	v_mov_b32_e32 v131, v189
	v_lshl_or_b32 v138, s2, 6, v7
	v_lshl_or_b32 v7, v7, 6, v17
	s_lshl_b32 s2, s2, 13
	v_and_b32_e32 v6, 32, v6
	s_and_b32 s0, s0, 0x60
	v_lshl_add_u64 v[8:9], s[14:15], 0, v[130:131]
	v_mov_b32_e32 v129, v189
	v_readlane_b32 s12, v253, 44
	v_bitop3_b32 v17, v7, s2, v6 bitop3:0xde
	s_lshl_b32 s2, s0, 7
	v_lshl_add_u64 v[10:11], s[14:15], 0, v[128:129]
	v_readlane_b32 s13, v253, 45
	v_bitop3_b32 v139, v7, s2, v6 bitop3:0xde
	s_add_i32 m0, s22, 0x18000
	v_lshl_add_u64 v[6:7], v[8:9], 0, s[92:93]
	v_lshl_add_u64 v[12:13], s[12:13], 0, v[130:131]
	s_waitcnt vmcnt(4)
	s_barrier
	global_load_lds_dwordx4 v[6:7], off
	v_lshl_add_u64 v[6:7], v[10:11], 0, s[92:93]
	s_add_i32 m0, s22, 0x1a000
	s_add_i32 s26, s22, 0x8000
	s_add_i32 s27, s22, 0xa000
	v_lshl_add_u64 v[14:15], s[12:13], 0, v[128:129]
	global_load_lds_dwordx4 v[6:7], off
	v_lshl_add_u64 v[6:7], v[12:13], 0, s[92:93]
	s_mov_b32 m0, s26
	s_add_u32 s2, s14, 0x40080
	global_load_lds_dwordx4 v[6:7], off
	v_lshl_add_u64 v[6:7], v[14:15], 0, s[92:93]
	s_mov_b32 m0, s27
	s_addc_u32 s3, s15, 0
	global_load_lds_dwordx4 v[6:7], off
	s_add_i32 m0, s22, 0x1c000
	v_lshl_add_u64 v[6:7], s[2:3], 0, v[130:131]
	global_load_lds_dwordx4 v[6:7], off
	v_lshl_add_u64 v[6:7], s[2:3], 0, v[128:129]
	s_add_i32 m0, s22, 0x1e000
	v_readlane_b32 s2, v253, 42
	global_load_lds_dwordx4 v[6:7], off
	v_lshlrev_b32_e32 v7, 14, v3
	v_and_b32_e32 v7, 0xffff8000, v7
	v_lshl_add_u32 v4, v4, 11, v7
	v_and_b32_e32 v3, 1, v3
	v_lshl_or_b32 v3, v3, 6, v4
	v_lshl_add_u32 v132, v5, 1, v3
	v_lshlrev_b32_e32 v3, 14, v0
	v_and_b32_e32 v3, 0xffff8000, v3
	s_waitcnt vmcnt(6)
	v_lshl_add_u32 v1, v1, 11, v3
	v_and_b32_e32 v0, 1, v0
	v_lshlrev_b32_e32 v6, 2, v16
	v_lshl_or_b32 v0, v0, 6, v1
	v_mov_b32_e32 v133, v189
	v_lshl_add_u32 v134, v2, 1, v0
	v_mov_b32_e32 v135, v189
	s_mov_b32 s28, 0
	v_add_u32_e32 v140, 0, v17
	s_lshl_b32 s0, s0, 1
	v_lshlrev_b32_e32 v188, 2, v6
	v_readlane_b32 s29, v253, 39
	s_mov_b32 s30, s2
	s_barrier
	v_readlane_b32 s3, v253, 43

.LBB0_184:
	s_add_u32 s14, s12, 0xfffc0080
	s_addc_u32 s15, s13, -1
	s_add_i32 s37, 0, 0x10000
	v_add_u32_e32 v136, s37, v139
	ds_read_b128 v[142:145], v136
	ds_read_b128 v[146:149], v136 offset:1024
	ds_read_b128 v[150:153], v136 offset:2048
	ds_read_b128 v[154:157], v136 offset:3072
	s_cmp_eq_u32 s36, 12
	s_cselect_b32 s17, s3, s15
	s_cselect_b32 s16, s31, s14
	s_cselect_b32 s15, s5, s35
	s_cselect_b32 s14, s33, s34
	v_lshl_add_u64 v[136:137], s[12:13], 0, v[132:133]
	s_add_i32 m0, s22, 0xc000
	ds_read_b128 v[158:161], v140
	ds_read_b128 v[162:165], v140 offset:1024
	ds_read_b128 v[166:169], v140 offset:2048
	ds_read_b128 v[170:173], v140 offset:3072
	ds_read_b128 v[174:177], v140 offset:4096
	ds_read_b128 v[178:181], v140 offset:5120
	ds_read_b128 v[182:185], v140 offset:6144
	ds_read_b128 v[190:193], v140 offset:7168
	global_load_lds_dwordx4 v[136:137], off
	v_lshl_add_u64 v[136:137], s[12:13], 0, v[134:135]
	s_add_i32 m0, s22, 0xe000
	s_nop 0
	global_load_lds_dwordx4 v[136:137], off
	s_waitcnt lgkmcnt(8)
	s_barrier
	s_waitcnt lgkmcnt(0)
	s_setprio 1
	s_waitcnt lgkmcnt(0)
	v_mfma_f32_16x16x32_bf16 v[124:127], v[142:145], v[158:161], v[124:127]
	v_mfma_f32_16x16x32_bf16 v[120:123], v[150:153], v[158:161], v[120:123]
	v_mfma_f32_16x16x32_bf16 v[108:111], v[142:145], v[166:169], v[108:111]
	v_mfma_f32_16x16x32_bf16 v[104:107], v[150:153], v[166:169], v[104:107]
	v_mfma_f32_16x16x32_bf16 v[92:95], v[142:145], v[174:177], v[92:95]
	v_mfma_f32_16x16x32_bf16 v[88:91], v[150:153], v[174:177], v[88:91]
	v_mfma_f32_16x16x32_bf16 v[76:79], v[142:145], v[182:185], v[76:79]
	v_mfma_f32_16x16x32_bf16 v[72:75], v[150:153], v[182:185], v[72:75]
	v_mfma_f32_16x16x32_bf16 v[124:127], v[146:149], v[162:165], v[124:127]
	v_mfma_f32_16x16x32_bf16 v[120:123], v[154:157], v[162:165], v[120:123]
	v_mfma_f32_16x16x32_bf16 v[108:111], v[146:149], v[170:173], v[108:111]
	v_mfma_f32_16x16x32_bf16 v[104:107], v[154:157], v[170:173], v[104:107]
	v_mfma_f32_16x16x32_bf16 v[92:95], v[146:149], v[178:181], v[92:95]
	v_mfma_f32_16x16x32_bf16 v[88:91], v[154:157], v[178:181], v[88:91]
	v_mfma_f32_16x16x32_bf16 v[76:79], v[146:149], v[190:193], v[76:79]
	v_mfma_f32_16x16x32_bf16 v[72:75], v[154:157], v[190:193], v[72:75]
	s_setprio 0
	s_barrier
	s_add_i32 s40, 0, 0x14000
	v_add_u32_e32 v136, s40, v139
	s_add_i32 s37, s37, s21
	ds_read_b128 v[194:197], v136
	ds_read_b128 v[198:201], v136 offset:1024
	ds_read_b128 v[216:219], v136 offset:2048
	ds_read_b128 v[220:223], v136 offset:3072
	v_lshl_add_u64 v[136:137], s[14:15], 0, v[130:131]
	s_mov_b32 m0, s37
	v_lshl_add_u64 v[186:187], s[14:15], 0, v[128:129]
	global_load_lds_dwordx4 v[136:137], off
	s_add_i32 m0, s37, 0x2000
	s_nop 0
	global_load_lds_dwordx4 v[186:187], off
	s_barrier
	s_waitcnt lgkmcnt(0)
	s_setprio 1
	s_waitcnt lgkmcnt(0)
	v_mfma_f32_16x16x32_bf16 v[116:119], v[194:197], v[158:161], v[116:119]
	v_mfma_f32_16x16x32_bf16 v[112:115], v[216:219], v[158:161], v[112:115]
	v_mfma_f32_16x16x32_bf16 v[100:103], v[194:197], v[166:169], v[100:103]
	v_mfma_f32_16x16x32_bf16 v[96:99], v[216:219], v[166:169], v[96:99]
	v_mfma_f32_16x16x32_bf16 v[84:87], v[194:197], v[174:177], v[84:87]
	v_mfma_f32_16x16x32_bf16 v[80:83], v[216:219], v[174:177], v[80:83]
	v_mfma_f32_16x16x32_bf16 v[68:71], v[194:197], v[182:185], v[68:71]
	v_mfma_f32_16x16x32_bf16 v[64:67], v[216:219], v[182:185], v[64:67]
	v_mfma_f32_16x16x32_bf16 v[116:119], v[198:201], v[162:165], v[116:119]
	v_mfma_f32_16x16x32_bf16 v[112:115], v[220:223], v[162:165], v[112:115]
	v_mfma_f32_16x16x32_bf16 v[100:103], v[198:201], v[170:173], v[100:103]
	v_mfma_f32_16x16x32_bf16 v[96:99], v[220:223], v[170:173], v[96:99]
	v_mfma_f32_16x16x32_bf16 v[84:87], v[198:201], v[178:181], v[84:87]
	v_mfma_f32_16x16x32_bf16 v[80:83], v[220:223], v[178:181], v[80:83]
	v_mfma_f32_16x16x32_bf16 v[68:71], v[198:201], v[190:193], v[68:71]
	v_mfma_f32_16x16x32_bf16 v[64:67], v[220:223], v[190:193], v[64:67]
	s_setprio 0
	s_mov_b32 m0, s22
	v_lshl_add_u64 v[202:203], s[16:17], 0, v[130:131]
	s_barrier
	ds_read_b128 v[158:161], v140 offset:16384
	ds_read_b128 v[162:165], v140 offset:17408
	ds_read_b128 v[166:169], v140 offset:18432
	ds_read_b128 v[170:173], v140 offset:19456
	ds_read_b128 v[174:177], v140 offset:20480
	ds_read_b128 v[178:181], v140 offset:21504
	ds_read_b128 v[182:185], v140 offset:22528
	ds_read_b128 v[190:193], v140 offset:23552
	global_load_lds_dwordx4 v[202:203], off
	v_lshl_add_u64 v[224:225], s[16:17], 0, v[128:129]
	s_mov_b32 m0, s23
	s_nop 0
	global_load_lds_dwordx4 v[224:225], off
	s_barrier
	s_waitcnt lgkmcnt(0)
	s_setprio 1
	s_waitcnt lgkmcnt(0)
	v_mfma_f32_16x16x32_bf16 v[60:63], v[142:145], v[158:161], v[60:63]
	v_mfma_f32_16x16x32_bf16 v[56:59], v[150:153], v[158:161], v[56:59]
	v_mfma_f32_16x16x32_bf16 v[44:47], v[142:145], v[166:169], v[44:47]
	v_mfma_f32_16x16x32_bf16 v[40:43], v[150:153], v[166:169], v[40:43]
	v_mfma_f32_16x16x32_bf16 v[28:31], v[142:145], v[174:177], v[28:31]
	v_mfma_f32_16x16x32_bf16 v[24:27], v[150:153], v[174:177], v[24:27]
	v_mfma_f32_16x16x32_bf16 v[12:15], v[142:145], v[182:185], v[12:15]
	v_mfma_f32_16x16x32_bf16 v[8:11], v[150:153], v[182:185], v[8:11]
	v_mfma_f32_16x16x32_bf16 v[60:63], v[146:149], v[162:165], v[60:63]
	v_mfma_f32_16x16x32_bf16 v[56:59], v[154:157], v[162:165], v[56:59]
	v_mfma_f32_16x16x32_bf16 v[44:47], v[146:149], v[170:173], v[44:47]
	v_mfma_f32_16x16x32_bf16 v[40:43], v[154:157], v[170:173], v[40:43]
	v_mfma_f32_16x16x32_bf16 v[28:31], v[146:149], v[178:181], v[28:31]
	v_mfma_f32_16x16x32_bf16 v[24:27], v[154:157], v[178:181], v[24:27]
	v_mfma_f32_16x16x32_bf16 v[12:15], v[146:149], v[190:193], v[12:15]
	v_mfma_f32_16x16x32_bf16 v[8:11], v[154:157], v[190:193], v[8:11]
	s_setprio 0
	s_barrier
	s_add_u32 s38, s14, 0x40000
	s_addc_u32 s39, s15, 0
	s_add_i32 s37, s40, s21
	v_lshl_add_u64 v[142:143], s[38:39], 0, v[130:131]
	s_mov_b32 m0, s37
	s_nop 0
	global_load_lds_dwordx4 v[142:143], off
	v_lshl_add_u64 v[142:143], s[38:39], 0, v[128:129]
	s_add_i32 m0, s37, 0x2000
	s_nop 0
	global_load_lds_dwordx4 v[142:143], off
	s_waitcnt vmcnt(6)
	s_barrier
	s_setprio 1
	v_mfma_f32_16x16x32_bf16 v[52:55], v[194:197], v[158:161], v[52:55]
	v_mfma_f32_16x16x32_bf16 v[48:51], v[216:219], v[158:161], v[48:51]
	v_mfma_f32_16x16x32_bf16 v[36:39], v[194:197], v[166:169], v[36:39]
	v_mfma_f32_16x16x32_bf16 v[32:35], v[216:219], v[166:169], v[32:35]
	v_mfma_f32_16x16x32_bf16 v[20:23], v[194:197], v[174:177], v[20:23]
	v_mfma_f32_16x16x32_bf16 v[16:19], v[216:219], v[174:177], v[16:19]
	v_mfma_f32_16x16x32_bf16 v[4:7], v[194:197], v[182:185], v[4:7]
	v_mfma_f32_16x16x32_bf16 v[0:3], v[216:219], v[182:185], v[0:3]
	v_mfma_f32_16x16x32_bf16 v[52:55], v[198:201], v[162:165], v[52:55]
	v_mfma_f32_16x16x32_bf16 v[48:51], v[220:223], v[162:165], v[48:51]
	v_mfma_f32_16x16x32_bf16 v[36:39], v[198:201], v[170:173], v[36:39]
	v_mfma_f32_16x16x32_bf16 v[32:35], v[220:223], v[170:173], v[32:35]
	v_mfma_f32_16x16x32_bf16 v[20:23], v[198:201], v[178:181], v[20:23]
	v_mfma_f32_16x16x32_bf16 v[16:19], v[220:223], v[178:181], v[16:19]
	v_mfma_f32_16x16x32_bf16 v[4:7], v[198:201], v[190:193], v[4:7]
	v_mfma_f32_16x16x32_bf16 v[0:3], v[220:223], v[190:193], v[0:3]
	s_setprio 0
	s_add_i32 s37, 0, 0x18000
	v_add_u32_e32 v141, s37, v139
	s_barrier
	ds_read_b128 v[142:145], v141
	ds_read_b128 v[146:149], v141 offset:1024
	ds_read_b128 v[150:153], v141 offset:2048
	ds_read_b128 v[154:157], v141 offset:3072
	s_add_u32 s16, s16, 0x40000
	s_addc_u32 s17, s17, 0
	s_mov_b32 m0, s24
	v_lshl_add_u64 v[194:195], s[16:17], 0, v[130:131]
	ds_read_b128 v[158:161], v140 offset:32768
	ds_read_b128 v[162:165], v140 offset:33792
	ds_read_b128 v[166:169], v140 offset:34816
	ds_read_b128 v[170:173], v140 offset:35840
	ds_read_b128 v[174:177], v140 offset:36864
	ds_read_b128 v[178:181], v140 offset:37888
	ds_read_b128 v[182:185], v140 offset:38912
	ds_read_b128 v[190:193], v140 offset:39936
	global_load_lds_dwordx4 v[194:195], off
	v_lshl_add_u64 v[194:195], s[16:17], 0, v[128:129]
	s_mov_b32 m0, s25
	s_nop 0
	global_load_lds_dwordx4 v[194:195], off
	s_waitcnt lgkmcnt(8)
	s_barrier
	s_waitcnt lgkmcnt(0)
	s_setprio 1
	s_waitcnt lgkmcnt(0)
	v_mfma_f32_16x16x32_bf16 v[124:127], v[142:145], v[158:161], v[124:127]
	v_mfma_f32_16x16x32_bf16 v[120:123], v[150:153], v[158:161], v[120:123]
	v_mfma_f32_16x16x32_bf16 v[108:111], v[142:145], v[166:169], v[108:111]
	v_mfma_f32_16x16x32_bf16 v[104:107], v[150:153], v[166:169], v[104:107]
	v_mfma_f32_16x16x32_bf16 v[92:95], v[142:145], v[174:177], v[92:95]
	v_mfma_f32_16x16x32_bf16 v[88:91], v[150:153], v[174:177], v[88:91]
	v_mfma_f32_16x16x32_bf16 v[76:79], v[142:145], v[182:185], v[76:79]
	v_mfma_f32_16x16x32_bf16 v[72:75], v[150:153], v[182:185], v[72:75]
	v_mfma_f32_16x16x32_bf16 v[124:127], v[146:149], v[162:165], v[124:127]
	v_mfma_f32_16x16x32_bf16 v[120:123], v[154:157], v[162:165], v[120:123]
	v_mfma_f32_16x16x32_bf16 v[108:111], v[146:149], v[170:173], v[108:111]
	v_mfma_f32_16x16x32_bf16 v[104:107], v[154:157], v[170:173], v[104:107]
	v_mfma_f32_16x16x32_bf16 v[92:95], v[146:149], v[178:181], v[92:95]
	v_mfma_f32_16x16x32_bf16 v[88:91], v[154:157], v[178:181], v[88:91]
	v_mfma_f32_16x16x32_bf16 v[76:79], v[146:149], v[190:193], v[76:79]
	v_mfma_f32_16x16x32_bf16 v[72:75], v[154:157], v[190:193], v[72:75]
	s_setprio 0
	s_barrier
	s_add_i32 s16, 0, 0x1c000
	s_add_i32 s17, s37, s21
	v_add_u32_e32 v141, s16, v139
	v_lshl_add_u64 v[136:137], v[136:137], 0, s[92:93]
	s_mov_b32 m0, s17
	ds_read_b128 v[194:197], v141
	ds_read_b128 v[198:201], v141 offset:1024
	ds_read_b128 v[216:219], v141 offset:2048
	ds_read_b128 v[220:223], v141 offset:3072
	global_load_lds_dwordx4 v[136:137], off
	v_lshl_add_u64 v[136:137], v[186:187], 0, s[92:93]
	s_add_i32 m0, s17, 0x2000
	s_nop 0
	global_load_lds_dwordx4 v[136:137], off
	s_barrier
	s_waitcnt lgkmcnt(0)
	s_setprio 1
	s_waitcnt lgkmcnt(0)
	v_mfma_f32_16x16x32_bf16 v[116:119], v[194:197], v[158:161], v[116:119]
	v_mfma_f32_16x16x32_bf16 v[112:115], v[216:219], v[158:161], v[112:115]
	v_mfma_f32_16x16x32_bf16 v[100:103], v[194:197], v[166:169], v[100:103]
	v_mfma_f32_16x16x32_bf16 v[96:99], v[216:219], v[166:169], v[96:99]
	v_mfma_f32_16x16x32_bf16 v[84:87], v[194:197], v[174:177], v[84:87]
	v_mfma_f32_16x16x32_bf16 v[80:83], v[216:219], v[174:177], v[80:83]
	v_mfma_f32_16x16x32_bf16 v[68:71], v[194:197], v[182:185], v[68:71]
	v_mfma_f32_16x16x32_bf16 v[64:67], v[216:219], v[182:185], v[64:67]
	v_mfma_f32_16x16x32_bf16 v[116:119], v[198:201], v[162:165], v[116:119]
	v_mfma_f32_16x16x32_bf16 v[112:115], v[220:223], v[162:165], v[112:115]
	v_mfma_f32_16x16x32_bf16 v[100:103], v[198:201], v[170:173], v[100:103]
	v_mfma_f32_16x16x32_bf16 v[96:99], v[220:223], v[170:173], v[96:99]
	v_mfma_f32_16x16x32_bf16 v[84:87], v[198:201], v[178:181], v[84:87]
	v_mfma_f32_16x16x32_bf16 v[80:83], v[220:223], v[178:181], v[80:83]
	v_mfma_f32_16x16x32_bf16 v[68:71], v[198:201], v[190:193], v[68:71]
	v_mfma_f32_16x16x32_bf16 v[64:67], v[220:223], v[190:193], v[64:67]
	s_setprio 0
	s_mov_b32 m0, s26
	v_lshl_add_u64 v[136:137], v[202:203], 0, s[92:93]
	s_barrier
	ds_read_b128 v[158:161], v140 offset:49152
	ds_read_b128 v[162:165], v140 offset:50176
	ds_read_b128 v[166:169], v140 offset:51200
	ds_read_b128 v[170:173], v140 offset:52224
	ds_read_b128 v[174:177], v140 offset:53248
	ds_read_b128 v[178:181], v140 offset:54272
	ds_read_b128 v[182:185], v140 offset:55296
	ds_read_b128 v[190:193], v140 offset:56320
	global_load_lds_dwordx4 v[136:137], off
	v_lshl_add_u64 v[136:137], v[224:225], 0, s[92:93]
	s_mov_b32 m0, s27
	s_nop 0
	global_load_lds_dwordx4 v[136:137], off
	s_barrier
	s_waitcnt lgkmcnt(0)
	s_setprio 1
	s_waitcnt lgkmcnt(0)
	v_mfma_f32_16x16x32_bf16 v[60:63], v[142:145], v[158:161], v[60:63]
	v_mfma_f32_16x16x32_bf16 v[56:59], v[150:153], v[158:161], v[56:59]
	v_mfma_f32_16x16x32_bf16 v[44:47], v[142:145], v[166:169], v[44:47]
	v_mfma_f32_16x16x32_bf16 v[40:43], v[150:153], v[166:169], v[40:43]
	v_mfma_f32_16x16x32_bf16 v[28:31], v[142:145], v[174:177], v[28:31]
	v_mfma_f32_16x16x32_bf16 v[24:27], v[150:153], v[174:177], v[24:27]
	v_mfma_f32_16x16x32_bf16 v[12:15], v[142:145], v[182:185], v[12:15]
	v_mfma_f32_16x16x32_bf16 v[8:11], v[150:153], v[182:185], v[8:11]
	v_mfma_f32_16x16x32_bf16 v[60:63], v[146:149], v[162:165], v[60:63]
	v_mfma_f32_16x16x32_bf16 v[56:59], v[154:157], v[162:165], v[56:59]
	v_mfma_f32_16x16x32_bf16 v[44:47], v[146:149], v[170:173], v[44:47]
	v_mfma_f32_16x16x32_bf16 v[40:43], v[154:157], v[170:173], v[40:43]
	v_mfma_f32_16x16x32_bf16 v[28:31], v[146:149], v[178:181], v[28:31]
	v_mfma_f32_16x16x32_bf16 v[24:27], v[154:157], v[178:181], v[24:27]
	v_mfma_f32_16x16x32_bf16 v[12:15], v[146:149], v[190:193], v[12:15]
	v_mfma_f32_16x16x32_bf16 v[8:11], v[154:157], v[190:193], v[8:11]
	s_setprio 0
	s_barrier
	s_add_u32 s14, s14, 0x40080
	s_addc_u32 s15, s15, 0
	s_add_i32 s16, s16, s21
	v_lshl_add_u64 v[136:137], s[14:15], 0, v[130:131]
	s_mov_b32 m0, s16
	s_nop 0
	global_load_lds_dwordx4 v[136:137], off
	v_lshl_add_u64 v[136:137], s[14:15], 0, v[128:129]
	s_add_i32 m0, s16, 0x2000
	s_nop 0
	global_load_lds_dwordx4 v[136:137], off
	s_waitcnt vmcnt(6)
	s_barrier
	s_setprio 1
	v_mfma_f32_16x16x32_bf16 v[52:55], v[194:197], v[158:161], v[52:55]
	v_mfma_f32_16x16x32_bf16 v[48:51], v[216:219], v[158:161], v[48:51]
	v_mfma_f32_16x16x32_bf16 v[36:39], v[194:197], v[166:169], v[36:39]
	v_mfma_f32_16x16x32_bf16 v[32:35], v[216:219], v[166:169], v[32:35]
	v_mfma_f32_16x16x32_bf16 v[20:23], v[194:197], v[174:177], v[20:23]
	v_mfma_f32_16x16x32_bf16 v[16:19], v[216:219], v[174:177], v[16:19]
	v_mfma_f32_16x16x32_bf16 v[4:7], v[194:197], v[182:185], v[4:7]
	v_mfma_f32_16x16x32_bf16 v[0:3], v[216:219], v[182:185], v[0:3]
	v_mfma_f32_16x16x32_bf16 v[52:55], v[198:201], v[162:165], v[52:55]
	v_mfma_f32_16x16x32_bf16 v[48:51], v[220:223], v[162:165], v[48:51]
	v_mfma_f32_16x16x32_bf16 v[36:39], v[198:201], v[170:173], v[36:39]
	v_mfma_f32_16x16x32_bf16 v[32:35], v[220:223], v[170:173], v[32:35]
	v_mfma_f32_16x16x32_bf16 v[20:23], v[198:201], v[178:181], v[20:23]
	v_mfma_f32_16x16x32_bf16 v[16:19], v[220:223], v[178:181], v[16:19]
	v_mfma_f32_16x16x32_bf16 v[4:7], v[198:201], v[190:193], v[4:7]
	v_mfma_f32_16x16x32_bf16 v[0:3], v[220:223], v[190:193], v[0:3]
	s_setprio 0
	s_add_i32 s36, s36, 2
	s_add_u32 s12, s12, 0x100
	s_addc_u32 s13, s13, 0
	s_add_u32 s34, s34, 0x100
	s_addc_u32 s35, s35, 0
	s_cmp_gt_u32 s36, 13
	s_barrier
	s_cbranch_scc0 .LBB0_184
	s_lshl_b32 s12, s29, 8
	v_mul_f32_e32 v124, 0xbfb8aa3b, v124
	v_lshl_add_u32 v141, s30, 8, v138
	s_ashr_i32 s13, s12, 31
	v_mov_b64_e32 v[136:137], s[94:95]
	s_movk_i32 s33, 0x1800
	v_exp_f32_e32 v144, v124
	v_mul_f32_e32 v124, 0xbfb8aa3b, v125
	v_mad_i64_i32 v[142:143], s[14:15], v141, s33, v[136:137]
	s_lshl_b64 s[12:13], s[12:13], 1
	v_exp_f32_e32 v145, v124
	v_lshl_add_u64 v[142:143], v[142:143], 0, s[12:13]
	v_lshl_add_u64 v[142:143], v[142:143], 0, s[0:1]
	v_mul_f32_e32 v120, 0xbfb8aa3b, v120
	v_lshl_add_u64 v[124:125], v[142:143], 0, v[188:189]
	v_add_f32_e32 v142, 1.0, v144
	v_exp_f32_e32 v144, v120
	v_mul_f32_e32 v120, 0xbfb8aa3b, v121
	v_add_f32_e32 v143, 1.0, v145
	v_mul_f32_e32 v126, 0xbfb8aa3b, v126
	v_mul_f32_e32 v127, 0xbfb8aa3b, v127
	v_exp_f32_e32 v121, v120
	v_mul_f32_e32 v122, 0xbfb8aa3b, v122
	v_rcp_f32_e32 v142, v142
	v_exp_f32_e32 v126, v126
	v_exp_f32_e32 v127, v127
	v_rcp_f32_e32 v143, v143
	v_exp_f32_e32 v122, v122
	v_mul_f32_e32 v123, 0xbfb8aa3b, v123
	v_exp_f32_e32 v123, v123
	v_add_f32_e32 v121, 1.0, v121
	v_add_f32_e32 v126, 1.0, v126
	v_add_f32_e32 v127, 1.0, v127
	v_cvt_pk_bf16_f32 v120, v142, v143
	v_rcp_f32_e32 v143, v121
	v_add_f32_e32 v121, 1.0, v122
	v_rcp_f32_e32 v126, v126
	v_rcp_f32_e32 v127, v127
	v_add_f32_e32 v142, 1.0, v144
	v_rcp_f32_e32 v122, v121
	v_add_f32_e32 v121, 1.0, v123
	v_rcp_f32_e32 v142, v142
	v_rcp_f32_e32 v123, v121
	v_mul_f32_e32 v116, 0xbfb8aa3b, v116
	v_mul_f32_e32 v117, 0xbfb8aa3b, v117
	v_exp_f32_e32 v116, v116
	v_exp_f32_e32 v117, v117
	v_cvt_pk_bf16_f32 v121, v126, v127
	v_cvt_pk_bf16_f32 v123, v122, v123
	v_cvt_pk_bf16_f32 v122, v142, v143
	v_mul_f32_e32 v112, 0xbfb8aa3b, v112
	global_store_dwordx4 v[124:125], v[120:123], off
	s_nop 1
	v_exp_f32_e32 v120, v112
	v_mul_f32_e32 v112, 0xbfb8aa3b, v113
	v_add_f32_e32 v116, 1.0, v116
	v_add_f32_e32 v117, 1.0, v117
	v_mul_f32_e32 v118, 0xbfb8aa3b, v118
	v_mul_f32_e32 v119, 0xbfb8aa3b, v119
	v_exp_f32_e32 v113, v112
	v_mul_f32_e32 v114, 0xbfb8aa3b, v114
	v_rcp_f32_e32 v116, v116
	v_exp_f32_e32 v118, v118
	v_exp_f32_e32 v119, v119
	v_rcp_f32_e32 v117, v117
	v_exp_f32_e32 v114, v114
	v_mul_f32_e32 v115, 0xbfb8aa3b, v115
	v_exp_f32_e32 v115, v115
	v_add_f32_e32 v113, 1.0, v113
	v_add_f32_e32 v118, 1.0, v118
	v_add_f32_e32 v119, 1.0, v119
	v_cvt_pk_bf16_f32 v112, v116, v117
	v_rcp_f32_e32 v117, v113
	v_add_f32_e32 v113, 1.0, v114
	v_rcp_f32_e32 v118, v118
	v_rcp_f32_e32 v119, v119
	v_add_f32_e32 v116, 1.0, v120
	v_rcp_f32_e32 v114, v113
	v_add_f32_e32 v113, 1.0, v115
	v_rcp_f32_e32 v116, v116
	v_rcp_f32_e32 v115, v113
	v_cvt_pk_bf16_f32 v113, v118, v119
	v_cvt_pk_bf16_f32 v115, v114, v115
	v_cvt_pk_bf16_f32 v114, v116, v117
	v_mul_f32_e32 v108, 0xbfb8aa3b, v108
	global_store_dwordx4 v[124:125], v[112:115], off offset:256
	s_nop 1
	v_or_b32_e32 v112, 16, v141
	v_exp_f32_e32 v114, v108
	v_mul_f32_e32 v108, 0xbfb8aa3b, v109
	v_mad_i64_i32 v[112:113], s[14:15], v112, s33, v[136:137]
	v_exp_f32_e32 v115, v108
	v_lshl_add_u64 v[112:113], v[112:113], 0, s[12:13]
	v_lshl_add_u64 v[112:113], v[112:113], 0, s[0:1]
	v_mul_f32_e32 v104, 0xbfb8aa3b, v104
	v_lshl_add_u64 v[108:109], v[112:113], 0, v[188:189]
	v_add_f32_e32 v112, 1.0, v114
	v_exp_f32_e32 v114, v104
	v_mul_f32_e32 v104, 0xbfb8aa3b, v105
	v_add_f32_e32 v113, 1.0, v115
	v_mul_f32_e32 v110, 0xbfb8aa3b, v110
	v_mul_f32_e32 v111, 0xbfb8aa3b, v111
	v_exp_f32_e32 v105, v104
	v_mul_f32_e32 v106, 0xbfb8aa3b, v106
	v_rcp_f32_e32 v112, v112
	v_exp_f32_e32 v110, v110
	v_exp_f32_e32 v111, v111
	v_rcp_f32_e32 v113, v113
	v_exp_f32_e32 v106, v106
	v_mul_f32_e32 v107, 0xbfb8aa3b, v107
	v_exp_f32_e32 v107, v107
	v_add_f32_e32 v105, 1.0, v105
	v_add_f32_e32 v110, 1.0, v110
	v_add_f32_e32 v111, 1.0, v111
	v_cvt_pk_bf16_f32 v104, v112, v113
	v_rcp_f32_e32 v113, v105
	v_add_f32_e32 v105, 1.0, v106
	v_rcp_f32_e32 v110, v110
	v_rcp_f32_e32 v111, v111
	v_add_f32_e32 v112, 1.0, v114
	v_rcp_f32_e32 v106, v105
	v_add_f32_e32 v105, 1.0, v107
	v_rcp_f32_e32 v112, v112
	v_rcp_f32_e32 v107, v105
	v_mul_f32_e32 v100, 0xbfb8aa3b, v100
	v_mul_f32_e32 v101, 0xbfb8aa3b, v101
	v_exp_f32_e32 v100, v100
	v_exp_f32_e32 v101, v101
	v_cvt_pk_bf16_f32 v105, v110, v111
	v_cvt_pk_bf16_f32 v107, v106, v107
	v_cvt_pk_bf16_f32 v106, v112, v113
	v_mul_f32_e32 v96, 0xbfb8aa3b, v96
	global_store_dwordx4 v[108:109], v[104:107], off
	s_nop 1
	v_exp_f32_e32 v104, v96
	v_mul_f32_e32 v96, 0xbfb8aa3b, v97
	v_add_f32_e32 v100, 1.0, v100
	v_add_f32_e32 v101, 1.0, v101
	v_mul_f32_e32 v102, 0xbfb8aa3b, v102
	v_mul_f32_e32 v103, 0xbfb8aa3b, v103
	v_exp_f32_e32 v97, v96
	v_mul_f32_e32 v98, 0xbfb8aa3b, v98
	v_rcp_f32_e32 v100, v100
	v_exp_f32_e32 v102, v102
	v_exp_f32_e32 v103, v103
	v_rcp_f32_e32 v101, v101
	v_exp_f32_e32 v98, v98
	v_mul_f32_e32 v99, 0xbfb8aa3b, v99
	v_exp_f32_e32 v99, v99
	v_add_f32_e32 v97, 1.0, v97
	v_add_f32_e32 v102, 1.0, v102
	v_add_f32_e32 v103, 1.0, v103
	v_cvt_pk_bf16_f32 v96, v100, v101
	v_rcp_f32_e32 v101, v97
	v_add_f32_e32 v97, 1.0, v98
	v_rcp_f32_e32 v102, v102
	v_rcp_f32_e32 v103, v103
	v_add_f32_e32 v100, 1.0, v104
	v_rcp_f32_e32 v98, v97
	v_add_f32_e32 v97, 1.0, v99
	v_rcp_f32_e32 v100, v100
	v_rcp_f32_e32 v99, v97
	v_cvt_pk_bf16_f32 v97, v102, v103
	v_cvt_pk_bf16_f32 v99, v98, v99
	v_cvt_pk_bf16_f32 v98, v100, v101
	v_mul_f32_e32 v92, 0xbfb8aa3b, v92
	global_store_dwordx4 v[108:109], v[96:99], off offset:256
	s_nop 1
	v_or_b32_e32 v96, 32, v141
	v_exp_f32_e32 v98, v92
	v_mul_f32_e32 v92, 0xbfb8aa3b, v93
	v_mad_i64_i32 v[96:97], s[14:15], v96, s33, v[136:137]
	v_exp_f32_e32 v99, v92
	v_lshl_add_u64 v[96:97], v[96:97], 0, s[12:13]
	v_lshl_add_u64 v[96:97], v[96:97], 0, s[0:1]
	v_mul_f32_e32 v88, 0xbfb8aa3b, v88
	v_lshl_add_u64 v[92:93], v[96:97], 0, v[188:189]
	v_add_f32_e32 v96, 1.0, v98
	v_exp_f32_e32 v98, v88
	v_mul_f32_e32 v88, 0xbfb8aa3b, v89
	v_add_f32_e32 v97, 1.0, v99
	v_mul_f32_e32 v94, 0xbfb8aa3b, v94
	v_mul_f32_e32 v95, 0xbfb8aa3b, v95
	v_exp_f32_e32 v89, v88
	v_mul_f32_e32 v90, 0xbfb8aa3b, v90
	v_rcp_f32_e32 v96, v96
	v_exp_f32_e32 v94, v94
	v_exp_f32_e32 v95, v95
	v_rcp_f32_e32 v97, v97
	v_exp_f32_e32 v90, v90
	v_mul_f32_e32 v91, 0xbfb8aa3b, v91
	v_exp_f32_e32 v91, v91
	v_add_f32_e32 v89, 1.0, v89
	v_add_f32_e32 v94, 1.0, v94
	v_add_f32_e32 v95, 1.0, v95
	v_cvt_pk_bf16_f32 v88, v96, v97
	v_rcp_f32_e32 v97, v89
	v_add_f32_e32 v89, 1.0, v90
	v_rcp_f32_e32 v94, v94
	v_rcp_f32_e32 v95, v95
	v_add_f32_e32 v96, 1.0, v98
	v_rcp_f32_e32 v90, v89
	v_add_f32_e32 v89, 1.0, v91
	v_rcp_f32_e32 v96, v96
	v_rcp_f32_e32 v91, v89
	v_mul_f32_e32 v84, 0xbfb8aa3b, v84
	v_mul_f32_e32 v85, 0xbfb8aa3b, v85
	v_exp_f32_e32 v84, v84
	v_exp_f32_e32 v85, v85
	v_cvt_pk_bf16_f32 v89, v94, v95
	v_cvt_pk_bf16_f32 v91, v90, v91
	v_cvt_pk_bf16_f32 v90, v96, v97
	v_mul_f32_e32 v80, 0xbfb8aa3b, v80
	global_store_dwordx4 v[92:93], v[88:91], off
	s_nop 1
	v_exp_f32_e32 v88, v80
	v_mul_f32_e32 v80, 0xbfb8aa3b, v81
	v_add_f32_e32 v84, 1.0, v84
	v_add_f32_e32 v85, 1.0, v85
	v_mul_f32_e32 v86, 0xbfb8aa3b, v86
	v_mul_f32_e32 v87, 0xbfb8aa3b, v87
	v_exp_f32_e32 v81, v80
	v_mul_f32_e32 v82, 0xbfb8aa3b, v82
	v_rcp_f32_e32 v84, v84
	v_exp_f32_e32 v86, v86
	v_exp_f32_e32 v87, v87
	v_rcp_f32_e32 v85, v85
	v_exp_f32_e32 v82, v82
	v_mul_f32_e32 v83, 0xbfb8aa3b, v83
	v_exp_f32_e32 v83, v83
	v_add_f32_e32 v81, 1.0, v81
	v_add_f32_e32 v86, 1.0, v86
	v_add_f32_e32 v87, 1.0, v87
	v_cvt_pk_bf16_f32 v80, v84, v85
	v_rcp_f32_e32 v85, v81
	v_add_f32_e32 v81, 1.0, v82
	v_rcp_f32_e32 v86, v86
	v_rcp_f32_e32 v87, v87
	v_add_f32_e32 v84, 1.0, v88
	v_rcp_f32_e32 v82, v81
	v_add_f32_e32 v81, 1.0, v83
	v_rcp_f32_e32 v84, v84
	v_rcp_f32_e32 v83, v81
	v_cvt_pk_bf16_f32 v81, v86, v87
	v_cvt_pk_bf16_f32 v83, v82, v83
	v_cvt_pk_bf16_f32 v82, v84, v85
	v_mul_f32_e32 v76, 0xbfb8aa3b, v76
	global_store_dwordx4 v[92:93], v[80:83], off offset:256
	s_nop 1
	v_or_b32_e32 v80, 48, v141
	v_exp_f32_e32 v82, v76
	v_mul_f32_e32 v76, 0xbfb8aa3b, v77
	v_mad_i64_i32 v[80:81], s[14:15], v80, s33, v[136:137]
	v_exp_f32_e32 v83, v76
	v_lshl_add_u64 v[80:81], v[80:81], 0, s[12:13]
	v_lshl_add_u64 v[80:81], v[80:81], 0, s[0:1]
	v_mul_f32_e32 v72, 0xbfb8aa3b, v72
	v_lshl_add_u64 v[76:77], v[80:81], 0, v[188:189]
	v_add_f32_e32 v80, 1.0, v82
	v_exp_f32_e32 v82, v72
	v_mul_f32_e32 v72, 0xbfb8aa3b, v73
	v_add_f32_e32 v81, 1.0, v83
	v_mul_f32_e32 v78, 0xbfb8aa3b, v78
	v_mul_f32_e32 v79, 0xbfb8aa3b, v79
	v_exp_f32_e32 v73, v72
	v_mul_f32_e32 v74, 0xbfb8aa3b, v74
	v_rcp_f32_e32 v80, v80
	v_exp_f32_e32 v78, v78
	v_exp_f32_e32 v79, v79
	v_rcp_f32_e32 v81, v81
	v_exp_f32_e32 v74, v74
	v_mul_f32_e32 v75, 0xbfb8aa3b, v75
	v_exp_f32_e32 v75, v75
	v_add_f32_e32 v73, 1.0, v73
	v_add_f32_e32 v78, 1.0, v78
	v_add_f32_e32 v79, 1.0, v79
	v_cvt_pk_bf16_f32 v72, v80, v81
	v_rcp_f32_e32 v81, v73
	v_add_f32_e32 v73, 1.0, v74
	v_rcp_f32_e32 v78, v78
	v_rcp_f32_e32 v79, v79
	v_add_f32_e32 v80, 1.0, v82
	v_rcp_f32_e32 v74, v73
	v_add_f32_e32 v73, 1.0, v75
	v_rcp_f32_e32 v80, v80
	v_rcp_f32_e32 v75, v73
	v_mul_f32_e32 v68, 0xbfb8aa3b, v68
	v_mul_f32_e32 v69, 0xbfb8aa3b, v69
	v_exp_f32_e32 v68, v68
	v_exp_f32_e32 v69, v69
	v_cvt_pk_bf16_f32 v73, v78, v79
	v_cvt_pk_bf16_f32 v75, v74, v75
	v_cvt_pk_bf16_f32 v74, v80, v81
	v_mul_f32_e32 v64, 0xbfb8aa3b, v64
	global_store_dwordx4 v[76:77], v[72:75], off
	s_nop 1
	v_exp_f32_e32 v72, v64
	v_mul_f32_e32 v64, 0xbfb8aa3b, v65
	v_add_f32_e32 v68, 1.0, v68
	v_add_f32_e32 v69, 1.0, v69
	v_mul_f32_e32 v70, 0xbfb8aa3b, v70
	v_mul_f32_e32 v71, 0xbfb8aa3b, v71
	v_exp_f32_e32 v65, v64
	v_mul_f32_e32 v66, 0xbfb8aa3b, v66
	v_rcp_f32_e32 v68, v68
	v_exp_f32_e32 v70, v70
	v_exp_f32_e32 v71, v71
	v_rcp_f32_e32 v69, v69
	v_exp_f32_e32 v66, v66
	v_mul_f32_e32 v67, 0xbfb8aa3b, v67
	v_exp_f32_e32 v67, v67
	v_add_f32_e32 v65, 1.0, v65
	v_add_f32_e32 v70, 1.0, v70
	v_add_f32_e32 v71, 1.0, v71
	v_cvt_pk_bf16_f32 v64, v68, v69
	v_rcp_f32_e32 v69, v65
	v_add_f32_e32 v65, 1.0, v66
	v_rcp_f32_e32 v70, v70
	v_rcp_f32_e32 v71, v71
	v_add_f32_e32 v68, 1.0, v72
	v_rcp_f32_e32 v66, v65
	v_add_f32_e32 v65, 1.0, v67
	v_rcp_f32_e32 v68, v68
	v_rcp_f32_e32 v67, v65
	v_cvt_pk_bf16_f32 v65, v70, v71
	v_cvt_pk_bf16_f32 v67, v66, v67
	v_cvt_pk_bf16_f32 v66, v68, v69
	v_mul_f32_e32 v60, 0xbfb8aa3b, v60
	global_store_dwordx4 v[76:77], v[64:67], off offset:256
	s_nop 1
	v_add_u32_e32 v64, 0x80, v141
	v_exp_f32_e32 v66, v60
	v_mul_f32_e32 v60, 0xbfb8aa3b, v61
	v_mad_i64_i32 v[64:65], s[14:15], v64, s33, v[136:137]
	v_exp_f32_e32 v67, v60
	v_lshl_add_u64 v[64:65], v[64:65], 0, s[12:13]
	v_lshl_add_u64 v[64:65], v[64:65], 0, s[0:1]
	v_mul_f32_e32 v56, 0xbfb8aa3b, v56
	v_lshl_add_u64 v[60:61], v[64:65], 0, v[188:189]
	v_add_f32_e32 v64, 1.0, v66
	v_exp_f32_e32 v66, v56
	v_mul_f32_e32 v56, 0xbfb8aa3b, v57
	v_add_f32_e32 v65, 1.0, v67
	v_mul_f32_e32 v62, 0xbfb8aa3b, v62
	v_mul_f32_e32 v63, 0xbfb8aa3b, v63
	v_exp_f32_e32 v57, v56
	v_mul_f32_e32 v58, 0xbfb8aa3b, v58
	v_rcp_f32_e32 v64, v64
	v_exp_f32_e32 v62, v62
	v_exp_f32_e32 v63, v63
	v_rcp_f32_e32 v65, v65
	v_exp_f32_e32 v58, v58
	v_mul_f32_e32 v59, 0xbfb8aa3b, v59
	v_exp_f32_e32 v59, v59
	v_add_f32_e32 v57, 1.0, v57
	v_add_f32_e32 v62, 1.0, v62
	v_add_f32_e32 v63, 1.0, v63
	v_cvt_pk_bf16_f32 v56, v64, v65
	v_rcp_f32_e32 v65, v57
	v_add_f32_e32 v57, 1.0, v58
	v_rcp_f32_e32 v62, v62
	v_rcp_f32_e32 v63, v63
	v_add_f32_e32 v64, 1.0, v66
	v_rcp_f32_e32 v58, v57
	v_add_f32_e32 v57, 1.0, v59
	v_rcp_f32_e32 v64, v64
	v_rcp_f32_e32 v59, v57
	v_mul_f32_e32 v52, 0xbfb8aa3b, v52
	v_mul_f32_e32 v53, 0xbfb8aa3b, v53
	v_exp_f32_e32 v52, v52
	v_exp_f32_e32 v53, v53
	v_cvt_pk_bf16_f32 v57, v62, v63
	v_cvt_pk_bf16_f32 v59, v58, v59
	v_cvt_pk_bf16_f32 v58, v64, v65
	v_mul_f32_e32 v48, 0xbfb8aa3b, v48
	global_store_dwordx4 v[60:61], v[56:59], off
	s_nop 1
	v_exp_f32_e32 v56, v48
	v_mul_f32_e32 v48, 0xbfb8aa3b, v49
	v_add_f32_e32 v52, 1.0, v52
	v_add_f32_e32 v53, 1.0, v53
	v_mul_f32_e32 v54, 0xbfb8aa3b, v54
	v_mul_f32_e32 v55, 0xbfb8aa3b, v55
	v_exp_f32_e32 v49, v48
	v_mul_f32_e32 v50, 0xbfb8aa3b, v50
	v_rcp_f32_e32 v52, v52
	v_exp_f32_e32 v54, v54
	v_exp_f32_e32 v55, v55
	v_rcp_f32_e32 v53, v53
	v_exp_f32_e32 v50, v50
	v_mul_f32_e32 v51, 0xbfb8aa3b, v51
	v_exp_f32_e32 v51, v51
	v_add_f32_e32 v49, 1.0, v49
	v_add_f32_e32 v54, 1.0, v54
	v_add_f32_e32 v55, 1.0, v55
	v_cvt_pk_bf16_f32 v48, v52, v53
	v_rcp_f32_e32 v53, v49
	v_add_f32_e32 v49, 1.0, v50
	v_rcp_f32_e32 v54, v54
	v_rcp_f32_e32 v55, v55
	v_add_f32_e32 v52, 1.0, v56
	v_rcp_f32_e32 v50, v49
	v_add_f32_e32 v49, 1.0, v51
	v_rcp_f32_e32 v52, v52
	v_rcp_f32_e32 v51, v49
	v_cvt_pk_bf16_f32 v49, v54, v55
	v_cvt_pk_bf16_f32 v51, v50, v51
	v_cvt_pk_bf16_f32 v50, v52, v53
	v_mul_f32_e32 v44, 0xbfb8aa3b, v44
	global_store_dwordx4 v[60:61], v[48:51], off offset:256
	s_nop 1
	v_add_u32_e32 v48, 0x90, v141
	v_exp_f32_e32 v50, v44
	v_mul_f32_e32 v44, 0xbfb8aa3b, v45
	v_mad_i64_i32 v[48:49], s[14:15], v48, s33, v[136:137]
	v_exp_f32_e32 v51, v44
	v_lshl_add_u64 v[48:49], v[48:49], 0, s[12:13]
	v_lshl_add_u64 v[48:49], v[48:49], 0, s[0:1]
	v_mul_f32_e32 v40, 0xbfb8aa3b, v40
	v_lshl_add_u64 v[44:45], v[48:49], 0, v[188:189]
	v_add_f32_e32 v48, 1.0, v50
	v_exp_f32_e32 v50, v40
	v_mul_f32_e32 v40, 0xbfb8aa3b, v41
	v_add_f32_e32 v49, 1.0, v51
	v_mul_f32_e32 v46, 0xbfb8aa3b, v46
	v_mul_f32_e32 v47, 0xbfb8aa3b, v47
	v_exp_f32_e32 v41, v40
	v_mul_f32_e32 v42, 0xbfb8aa3b, v42
	v_rcp_f32_e32 v48, v48
	v_exp_f32_e32 v46, v46
	v_exp_f32_e32 v47, v47
	v_rcp_f32_e32 v49, v49
	v_exp_f32_e32 v42, v42
	v_mul_f32_e32 v43, 0xbfb8aa3b, v43
	v_exp_f32_e32 v43, v43
	v_add_f32_e32 v41, 1.0, v41
	v_add_f32_e32 v46, 1.0, v46
	v_add_f32_e32 v47, 1.0, v47
	v_cvt_pk_bf16_f32 v40, v48, v49
	v_rcp_f32_e32 v49, v41
	v_add_f32_e32 v41, 1.0, v42
	v_rcp_f32_e32 v46, v46
	v_rcp_f32_e32 v47, v47
	v_add_f32_e32 v48, 1.0, v50
	v_rcp_f32_e32 v42, v41
	v_add_f32_e32 v41, 1.0, v43
	v_rcp_f32_e32 v48, v48
	v_rcp_f32_e32 v43, v41
	v_mul_f32_e32 v36, 0xbfb8aa3b, v36
	v_mul_f32_e32 v37, 0xbfb8aa3b, v37
	v_exp_f32_e32 v36, v36
	v_exp_f32_e32 v37, v37
	v_cvt_pk_bf16_f32 v41, v46, v47
	v_cvt_pk_bf16_f32 v43, v42, v43
	v_cvt_pk_bf16_f32 v42, v48, v49
	v_mul_f32_e32 v32, 0xbfb8aa3b, v32
	global_store_dwordx4 v[44:45], v[40:43], off
	s_nop 1
	v_exp_f32_e32 v40, v32
	v_mul_f32_e32 v32, 0xbfb8aa3b, v33
	v_add_f32_e32 v36, 1.0, v36
	v_add_f32_e32 v37, 1.0, v37
	v_mul_f32_e32 v38, 0xbfb8aa3b, v38
	v_mul_f32_e32 v39, 0xbfb8aa3b, v39
	v_exp_f32_e32 v33, v32
	v_mul_f32_e32 v34, 0xbfb8aa3b, v34
	v_rcp_f32_e32 v36, v36
	v_exp_f32_e32 v38, v38
	v_exp_f32_e32 v39, v39
	v_rcp_f32_e32 v37, v37
	v_exp_f32_e32 v34, v34
	v_mul_f32_e32 v35, 0xbfb8aa3b, v35
	v_exp_f32_e32 v35, v35
	v_add_f32_e32 v33, 1.0, v33
	v_add_f32_e32 v38, 1.0, v38
	v_add_f32_e32 v39, 1.0, v39
	v_cvt_pk_bf16_f32 v32, v36, v37
	v_rcp_f32_e32 v37, v33
	v_add_f32_e32 v33, 1.0, v34
	v_rcp_f32_e32 v38, v38
	v_rcp_f32_e32 v39, v39
	v_add_f32_e32 v36, 1.0, v40
	v_rcp_f32_e32 v34, v33
	v_add_f32_e32 v33, 1.0, v35
	v_rcp_f32_e32 v36, v36
	v_rcp_f32_e32 v35, v33
	v_cvt_pk_bf16_f32 v33, v38, v39
	v_cvt_pk_bf16_f32 v35, v34, v35
	v_cvt_pk_bf16_f32 v34, v36, v37
	v_mul_f32_e32 v28, 0xbfb8aa3b, v28
	global_store_dwordx4 v[44:45], v[32:35], off offset:256
	s_nop 1
	v_add_u32_e32 v32, 0xa0, v141
	v_exp_f32_e32 v34, v28
	v_mul_f32_e32 v28, 0xbfb8aa3b, v29
	v_mad_i64_i32 v[32:33], s[14:15], v32, s33, v[136:137]
	v_exp_f32_e32 v35, v28
	v_lshl_add_u64 v[32:33], v[32:33], 0, s[12:13]
	v_lshl_add_u64 v[32:33], v[32:33], 0, s[0:1]
	v_mul_f32_e32 v24, 0xbfb8aa3b, v24
	v_lshl_add_u64 v[28:29], v[32:33], 0, v[188:189]
	v_add_f32_e32 v32, 1.0, v34
	v_exp_f32_e32 v34, v24
	v_mul_f32_e32 v24, 0xbfb8aa3b, v25
	v_add_f32_e32 v33, 1.0, v35
	v_mul_f32_e32 v30, 0xbfb8aa3b, v30
	v_mul_f32_e32 v31, 0xbfb8aa3b, v31
	v_exp_f32_e32 v25, v24
	v_mul_f32_e32 v26, 0xbfb8aa3b, v26
	v_rcp_f32_e32 v32, v32
	v_exp_f32_e32 v30, v30
	v_exp_f32_e32 v31, v31
	v_rcp_f32_e32 v33, v33
	v_exp_f32_e32 v26, v26
	v_mul_f32_e32 v27, 0xbfb8aa3b, v27
	v_exp_f32_e32 v27, v27
	v_add_f32_e32 v25, 1.0, v25
	v_add_f32_e32 v30, 1.0, v30
	v_add_f32_e32 v31, 1.0, v31
	v_cvt_pk_bf16_f32 v24, v32, v33
	v_rcp_f32_e32 v33, v25
	v_add_f32_e32 v25, 1.0, v26
	v_rcp_f32_e32 v30, v30
	v_rcp_f32_e32 v31, v31
	v_add_f32_e32 v32, 1.0, v34
	v_rcp_f32_e32 v26, v25
	v_add_f32_e32 v25, 1.0, v27
	v_rcp_f32_e32 v32, v32
	v_rcp_f32_e32 v27, v25
	v_mul_f32_e32 v20, 0xbfb8aa3b, v20
	v_mul_f32_e32 v21, 0xbfb8aa3b, v21
	v_exp_f32_e32 v20, v20
	v_exp_f32_e32 v21, v21
	v_cvt_pk_bf16_f32 v25, v30, v31
	v_cvt_pk_bf16_f32 v27, v26, v27
	v_cvt_pk_bf16_f32 v26, v32, v33
	v_mul_f32_e32 v16, 0xbfb8aa3b, v16
	global_store_dwordx4 v[28:29], v[24:27], off
	s_nop 1
	v_exp_f32_e32 v24, v16
	v_mul_f32_e32 v16, 0xbfb8aa3b, v17
	v_add_f32_e32 v20, 1.0, v20
	v_add_f32_e32 v21, 1.0, v21
	v_mul_f32_e32 v22, 0xbfb8aa3b, v22
	v_mul_f32_e32 v23, 0xbfb8aa3b, v23
	v_exp_f32_e32 v17, v16
	v_mul_f32_e32 v18, 0xbfb8aa3b, v18
	v_rcp_f32_e32 v20, v20
	v_exp_f32_e32 v22, v22
	v_exp_f32_e32 v23, v23
	v_rcp_f32_e32 v21, v21
	v_exp_f32_e32 v18, v18
	v_mul_f32_e32 v19, 0xbfb8aa3b, v19
	v_exp_f32_e32 v19, v19
	v_add_f32_e32 v17, 1.0, v17
	v_add_f32_e32 v22, 1.0, v22
	v_add_f32_e32 v23, 1.0, v23
	v_cvt_pk_bf16_f32 v16, v20, v21
	v_rcp_f32_e32 v21, v17
	v_add_f32_e32 v17, 1.0, v18
	v_rcp_f32_e32 v22, v22
	v_rcp_f32_e32 v23, v23
	v_add_f32_e32 v20, 1.0, v24
	v_rcp_f32_e32 v18, v17
	v_add_f32_e32 v17, 1.0, v19
	v_rcp_f32_e32 v20, v20
	v_rcp_f32_e32 v19, v17
	v_cvt_pk_bf16_f32 v17, v22, v23
	v_cvt_pk_bf16_f32 v19, v18, v19
	v_cvt_pk_bf16_f32 v18, v20, v21
	v_mul_f32_e32 v12, 0xbfb8aa3b, v12
	global_store_dwordx4 v[28:29], v[16:19], off offset:256
	s_nop 1
	v_add_u32_e32 v16, 0xb0, v141
	v_exp_f32_e32 v18, v12
	v_mul_f32_e32 v12, 0xbfb8aa3b, v13
	v_mad_i64_i32 v[16:17], s[14:15], v16, s33, v[136:137]
	v_exp_f32_e32 v19, v12
	v_lshl_add_u64 v[16:17], v[16:17], 0, s[12:13]
	v_lshl_add_u64 v[16:17], v[16:17], 0, s[0:1]
	v_mul_f32_e32 v8, 0xbfb8aa3b, v8
	v_lshl_add_u64 v[12:13], v[16:17], 0, v[188:189]
	v_add_f32_e32 v16, 1.0, v18
	v_exp_f32_e32 v18, v8
	v_mul_f32_e32 v8, 0xbfb8aa3b, v9
	v_add_f32_e32 v17, 1.0, v19
	v_mul_f32_e32 v14, 0xbfb8aa3b, v14
	v_mul_f32_e32 v15, 0xbfb8aa3b, v15
	v_exp_f32_e32 v9, v8
	v_mul_f32_e32 v10, 0xbfb8aa3b, v10
	v_rcp_f32_e32 v16, v16
	v_exp_f32_e32 v14, v14
	v_exp_f32_e32 v15, v15
	v_rcp_f32_e32 v17, v17
	v_exp_f32_e32 v10, v10
	v_mul_f32_e32 v11, 0xbfb8aa3b, v11
	v_exp_f32_e32 v11, v11
	v_add_f32_e32 v9, 1.0, v9
	v_add_f32_e32 v14, 1.0, v14
	v_add_f32_e32 v15, 1.0, v15
	v_cvt_pk_bf16_f32 v8, v16, v17
	v_rcp_f32_e32 v17, v9
	v_add_f32_e32 v9, 1.0, v10
	v_rcp_f32_e32 v14, v14
	v_rcp_f32_e32 v15, v15
	v_add_f32_e32 v16, 1.0, v18
	v_rcp_f32_e32 v10, v9
	v_add_f32_e32 v9, 1.0, v11
	v_rcp_f32_e32 v16, v16
	v_rcp_f32_e32 v11, v9
	v_mul_f32_e32 v4, 0xbfb8aa3b, v4
	v_mul_f32_e32 v5, 0xbfb8aa3b, v5
	v_exp_f32_e32 v4, v4
	v_exp_f32_e32 v5, v5
	v_cvt_pk_bf16_f32 v9, v14, v15
	v_cvt_pk_bf16_f32 v11, v10, v11
	v_cvt_pk_bf16_f32 v10, v16, v17
	v_mul_f32_e32 v0, 0xbfb8aa3b, v0
	global_store_dwordx4 v[12:13], v[8:11], off
	s_nop 1
	v_exp_f32_e32 v8, v0
	v_mul_f32_e32 v0, 0xbfb8aa3b, v1
	v_add_f32_e32 v4, 1.0, v4
	v_add_f32_e32 v5, 1.0, v5
	v_mul_f32_e32 v6, 0xbfb8aa3b, v6
	v_mul_f32_e32 v7, 0xbfb8aa3b, v7
	v_exp_f32_e32 v1, v0
	v_mul_f32_e32 v2, 0xbfb8aa3b, v2
	v_rcp_f32_e32 v4, v4
	v_exp_f32_e32 v6, v6
	v_exp_f32_e32 v7, v7
	v_rcp_f32_e32 v5, v5
	v_exp_f32_e32 v2, v2
	v_mul_f32_e32 v3, 0xbfb8aa3b, v3
	v_exp_f32_e32 v3, v3
	v_add_f32_e32 v1, 1.0, v1
	v_add_f32_e32 v6, 1.0, v6
	v_add_f32_e32 v7, 1.0, v7
	v_cvt_pk_bf16_f32 v0, v4, v5
	v_rcp_f32_e32 v5, v1
	v_add_f32_e32 v1, 1.0, v2
	v_rcp_f32_e32 v6, v6
	v_rcp_f32_e32 v7, v7
	v_add_f32_e32 v4, 1.0, v8
	v_rcp_f32_e32 v2, v1
	v_add_f32_e32 v1, 1.0, v3
	v_rcp_f32_e32 v4, v4
	v_rcp_f32_e32 v3, v1
	v_cvt_pk_bf16_f32 v1, v6, v7
	v_cvt_pk_bf16_f32 v3, v2, v3
	v_cvt_pk_bf16_f32 v2, v4, v5
	s_and_b64 vcc, exec, s[6:7]
	s_mov_b32 s29, s4
	s_mov_b32 s30, s2
	s_mov_b64 s[14:15], s[10:11]
	s_mov_b64 s[12:13], s[8:9]
	global_store_dwordx4 v[12:13], v[0:3], off offset:256
	s_nop 1
	s_cbranch_vccz .LBB0_181
	s_waitcnt vmcnt(0)
	s_cmpk_gt_u32 s18, 0xff
	s_cbranch_scc1 .LBB0_188
	s_barrier
